# q/kv up-projection tiles re-assigned by cost: workgroups with three tiles take three q (K=512) tiles, those with four take three kv (K=256) + one q, instead of two + two
# speedup vs baseline: 1.0065x; 1.0065x over previous
.LBB0_804:
	s_mov_b32 s98, s20
	v_readlane_b32 s0, v254, 1
	s_cmpk_eq_u32 s0, 0x100
	s_cbranch_scc0 .Lrm_done
	s_and_b32 s0, s20, 0xff
	s_lshr_b32 s1, s20, 8
	v_readlane_b32 s99, v255, 14
	s_sub_u32 s99, s99, 0x300
	s_sub_u32 vcc_lo, 0x100, s99
	s_mul_i32 vcc_lo, vcc_lo, 3
	s_cmp_lt_u32 s0, s99
	s_cbranch_scc1 .Lrm_four
	s_sub_u32 s0, s0, s99
	s_mul_i32 s0, s0, 3
	s_add_u32 s0, s0, s1
	s_add_u32 s20, s0, 0x220
	s_branch .Lrm_done
.Lrm_four:
	s_mul_i32 vcc_hi, s99, 3
	s_cmpk_eq_u32 s1, 3
	s_cbranch_scc1 .Lrm_k3
	s_mul_i32 s1, s1, s99
	s_add_u32 s20, s0, s1
	s_cmpk_lt_u32 s20, 0x220
	s_cbranch_scc1 .Lrm_done
	s_add_u32 s20, s20, vcc_lo
	s_add_u32 s20, s20, s99
	s_branch .Lrm_done
.Lrm_k3:
	s_sub_i32 s1, 0x220, vcc_hi
	s_max_i32 s1, s1, 0
	s_cmp_lt_u32 s0, s1
	s_cbranch_scc0 .Lrm_k3q
	s_add_u32 s20, vcc_hi, s0
	s_branch .Lrm_done
.Lrm_k3q:
	s_sub_u32 s0, s0, s1
	s_add_u32 s0, s0, vcc_lo
	s_add_u32 s20, s0, 0x220
